# adds: ticket prefetch also during the fused HGRN2 units
# baseline (speedup 1.0000x reference)
; __global__ void __launch_bounds__(512, 2) fwd_megakernel(Params P) {
;     ...
;                 if (tid == 0) *slot = (int)atomicAdd(cnt, 1u);
;                 __syncthreads();
;                 const int pt = *slot;
;                 __syncthreads();
;                 if (pt >= T_FX) break;
;                 int tk;
;                 { constexpr int A1 = 1408, P1_ = T_HP + A1, P2_ = P1_ + 32 * NSEG, P3_ = P2_ + 128, P4_ = P3_ + 64, P5_ = P4_ + 16;
;                   if (pt < P1_) tk = pt;
;                   else if (pt < P2_) tk = T_SO + (pt - P1_);
;                   else if (pt < P3_) tk = T_AP + (pt - P2_);
;                   else if (pt < P4_) tk = T_AS + (pt - P3_);
;                   else if (pt < P5_) tk = T_HSM + (pt - P4_);
;                   else tk = T_HP + A1 + (pt - P5_); }
.LBB0_546:
	s_or_b64 exec, exec, s[22:23]
	v_readlane_b32 s3, v243, 49
	s_waitcnt lgkmcnt(0)
	s_barrier
	v_mov_b32_e32 v0, s3
	ds_read_b32 v0, v0
	s_movk_i32 s5, 0xacf
	s_waitcnt lgkmcnt(0)
	s_barrier
	v_cmp_lt_i32_e64 s[38:39], s5, v0
	v_readfirstlane_b32 s7, v0
	s_and_b64 vcc, exec, s[38:39]
	s_cbranch_vccnz .LBB0_541
	s_mov_b32 s100, 0
	s_cmpk_lt_i32 s7, 0x680
	s_cbranch_scc1 .Ltk_pf
	s_cmpk_lt_i32 s7, 0x850
	s_cbranch_scc1 .Ltk_nopf
